# nt on W2 A-operand (U) LDS-DMA loads
# baseline (speedup 1.0000x reference)
.LBB0_92:
	v_add_u32_e32 v96, s30, v179
	v_add_u32_e32 v176, s31, v179
	ds_read_b128 v[76:79], v96
	ds_read_b128 v[84:87], v96 offset:1024
	ds_read_b128 v[88:91], v96 offset:2048
	s_waitcnt lgkmcnt(0)
	ds_read_b128 v[96:99], v96 offset:3072
	ds_read_b128 v[172:175], v176
	ds_read_b128 v[182:185], v176 offset:1024
	ds_read_b128 v[190:193], v176 offset:2048
	ds_read_b128 v[194:197], v176 offset:3072
	s_add_u32 s16, s48, 0xfff00080
	s_addc_u32 s17, s49, -1
	s_cmp_eq_u32 s89, 60
	s_cselect_b32 s57, s25, s17
	s_cselect_b32 s56, s85, s16
	s_cselect_b32 s17, s11, s88
	s_cselect_b32 s16, s86, s87
	v_lshl_add_u64 v[176:177], s[48:49], 0, v[168:169]
	s_add_i32 m0, s47, 0xc000
	ds_read_b128 v[198:201], v181
	ds_read_b128 v[202:205], v181 offset:1024
	ds_read_b128 v[206:209], v181 offset:2048
	ds_read_b128 v[210:213], v181 offset:3072
	ds_read_b128 v[214:217], v181 offset:4096
	ds_read_b128 v[218:221], v181 offset:5120
	ds_read_b128 v[222:225], v181 offset:6144
	ds_read_b128 v[226:229], v181 offset:7168
	global_load_lds_dwordx4 v[176:177], off nt
	v_lshl_add_u64 v[176:177], s[48:49], 0, v[170:171]
	s_add_i32 m0, s47, 0xe000
	s_nop 0
	global_load_lds_dwordx4 v[176:177], off nt
	s_waitcnt vmcnt(8)
	s_waitcnt lgkmcnt(0)
	s_barrier
	s_setprio 1
	s_waitcnt lgkmcnt(0)
	v_mfma_f32_16x16x32_bf16 v[140:143], v[76:79], v[198:201], v[140:143]
	v_mfma_f32_16x16x32_bf16 v[136:139], v[88:91], v[198:201], v[136:139]
	v_mfma_f32_16x16x32_bf16 v[124:127], v[76:79], v[206:209], v[124:127]
	v_mfma_f32_16x16x32_bf16 v[120:123], v[88:91], v[206:209], v[120:123]
	v_mfma_f32_16x16x32_bf16 v[108:111], v[76:79], v[214:217], v[108:111]
	v_mfma_f32_16x16x32_bf16 v[104:107], v[88:91], v[214:217], v[104:107]
	v_mfma_f32_16x16x32_bf16 v[80:83], v[76:79], v[222:225], v[80:83]
	v_mfma_f32_16x16x32_bf16 v[72:75], v[88:91], v[222:225], v[72:75]
	v_mfma_f32_16x16x32_bf16 v[140:143], v[84:87], v[202:205], v[140:143]
	v_mfma_f32_16x16x32_bf16 v[136:139], v[96:99], v[202:205], v[136:139]
	v_mfma_f32_16x16x32_bf16 v[124:127], v[84:87], v[210:213], v[124:127]
	v_mfma_f32_16x16x32_bf16 v[120:123], v[96:99], v[210:213], v[120:123]
	v_mfma_f32_16x16x32_bf16 v[108:111], v[84:87], v[218:221], v[108:111]
	v_mfma_f32_16x16x32_bf16 v[104:107], v[96:99], v[218:221], v[104:107]
	v_mfma_f32_16x16x32_bf16 v[80:83], v[84:87], v[226:229], v[80:83]
	v_mfma_f32_16x16x32_bf16 v[72:75], v[96:99], v[226:229], v[72:75]
	s_setprio 0
	s_setprio 1
	v_mfma_f32_16x16x32_bf16 v[132:135], v[172:175], v[198:201], v[132:135]
	v_mfma_f32_16x16x32_bf16 v[128:131], v[190:193], v[198:201], v[128:131]
	v_mfma_f32_16x16x32_bf16 v[116:119], v[172:175], v[206:209], v[116:119]
	v_mfma_f32_16x16x32_bf16 v[112:115], v[190:193], v[206:209], v[112:115]
	v_mfma_f32_16x16x32_bf16 v[100:103], v[172:175], v[214:217], v[100:103]
	v_mfma_f32_16x16x32_bf16 v[92:95], v[190:193], v[214:217], v[92:95]
	v_mfma_f32_16x16x32_bf16 v[68:71], v[172:175], v[222:225], v[68:71]
	v_mfma_f32_16x16x32_bf16 v[64:67], v[190:193], v[222:225], v[64:67]
	v_mfma_f32_16x16x32_bf16 v[132:135], v[182:185], v[202:205], v[132:135]
	v_mfma_f32_16x16x32_bf16 v[128:131], v[194:197], v[202:205], v[128:131]
	v_mfma_f32_16x16x32_bf16 v[116:119], v[182:185], v[210:213], v[116:119]
	v_mfma_f32_16x16x32_bf16 v[112:115], v[194:197], v[210:213], v[112:115]
	v_mfma_f32_16x16x32_bf16 v[100:103], v[182:185], v[218:221], v[100:103]
	v_mfma_f32_16x16x32_bf16 v[92:95], v[194:197], v[218:221], v[92:95]
	v_mfma_f32_16x16x32_bf16 v[68:71], v[182:185], v[226:229], v[68:71]
	v_mfma_f32_16x16x32_bf16 v[64:67], v[194:197], v[226:229], v[64:67]
	s_setprio 0
	s_barrier
	s_mov_b32 m0, s34
	v_lshl_add_u64 v[176:177], s[16:17], 0, v[148:149]
	s_add_u32 s90, s16, 0x40000
	ds_read_b128 v[198:201], v181 offset:16384
	ds_read_b128 v[202:205], v181 offset:17408
	ds_read_b128 v[206:209], v181 offset:18432
	ds_read_b128 v[210:213], v181 offset:19456
	ds_read_b128 v[214:217], v181 offset:20480
	ds_read_b128 v[218:221], v181 offset:21504
	ds_read_b128 v[222:225], v181 offset:22528
	ds_read_b128 v[226:229], v181 offset:23552
	global_load_lds_dwordx4 v[176:177], off
	v_lshl_add_u64 v[186:187], s[16:17], 0, v[166:167]
	s_mov_b32 m0, s35
	s_addc_u32 s91, s17, 0
	global_load_lds_dwordx4 v[186:187], off
	v_lshl_add_u64 v[230:231], s[90:91], 0, v[148:149]
	s_mov_b32 m0, s43
	v_lshl_add_u64 v[232:233], s[56:57], 0, v[164:165]
	global_load_lds_dwordx4 v[230:231], off
	v_lshl_add_u64 v[230:231], s[90:91], 0, v[166:167]
	s_mov_b32 m0, s45
	s_nop 0
	global_load_lds_dwordx4 v[230:231], off
	v_lshl_add_u64 v[230:231], s[56:57], 0, v[146:147]
	s_mov_b32 m0, s47
	s_nop 0
	global_load_lds_dwordx4 v[230:231], off nt
	s_mov_b32 m0, s62
	s_nop 0
	global_load_lds_dwordx4 v[232:233], off nt
	s_waitcnt vmcnt(8)
	s_waitcnt lgkmcnt(0)
	s_barrier
	s_setprio 1
	s_waitcnt lgkmcnt(0)
	v_mfma_f32_16x16x32_bf16 v[60:63], v[76:79], v[198:201], v[60:63]
	v_mfma_f32_16x16x32_bf16 v[56:59], v[88:91], v[198:201], v[56:59]
	v_mfma_f32_16x16x32_bf16 v[44:47], v[76:79], v[206:209], v[44:47]
	v_mfma_f32_16x16x32_bf16 v[40:43], v[88:91], v[206:209], v[40:43]
	v_mfma_f32_16x16x32_bf16 v[28:31], v[76:79], v[214:217], v[28:31]
	v_mfma_f32_16x16x32_bf16 v[24:27], v[88:91], v[214:217], v[24:27]
	v_mfma_f32_16x16x32_bf16 v[12:15], v[76:79], v[222:225], v[12:15]
	v_mfma_f32_16x16x32_bf16 v[8:11], v[88:91], v[222:225], v[8:11]
	v_mfma_f32_16x16x32_bf16 v[60:63], v[84:87], v[202:205], v[60:63]
	v_mfma_f32_16x16x32_bf16 v[56:59], v[96:99], v[202:205], v[56:59]
	v_mfma_f32_16x16x32_bf16 v[44:47], v[84:87], v[210:213], v[44:47]
	v_mfma_f32_16x16x32_bf16 v[40:43], v[96:99], v[210:213], v[40:43]
	v_mfma_f32_16x16x32_bf16 v[28:31], v[84:87], v[218:221], v[28:31]
	v_mfma_f32_16x16x32_bf16 v[24:27], v[96:99], v[218:221], v[24:27]
	v_mfma_f32_16x16x32_bf16 v[12:15], v[84:87], v[226:229], v[12:15]
	v_mfma_f32_16x16x32_bf16 v[8:11], v[96:99], v[226:229], v[8:11]
	s_setprio 0
	s_setprio 1
	v_mfma_f32_16x16x32_bf16 v[52:55], v[172:175], v[198:201], v[52:55]
	v_mfma_f32_16x16x32_bf16 v[48:51], v[190:193], v[198:201], v[48:51]
	v_mfma_f32_16x16x32_bf16 v[36:39], v[172:175], v[206:209], v[36:39]
	v_mfma_f32_16x16x32_bf16 v[32:35], v[190:193], v[206:209], v[32:35]
	v_mfma_f32_16x16x32_bf16 v[20:23], v[172:175], v[214:217], v[20:23]
	v_mfma_f32_16x16x32_bf16 v[16:19], v[190:193], v[214:217], v[16:19]
	v_mfma_f32_16x16x32_bf16 v[4:7], v[172:175], v[222:225], v[4:7]
	v_mfma_f32_16x16x32_bf16 v[0:3], v[190:193], v[222:225], v[0:3]
	v_mfma_f32_16x16x32_bf16 v[52:55], v[182:185], v[202:205], v[52:55]
	v_mfma_f32_16x16x32_bf16 v[48:51], v[194:197], v[202:205], v[48:51]
	v_mfma_f32_16x16x32_bf16 v[36:39], v[182:185], v[210:213], v[36:39]
	v_mfma_f32_16x16x32_bf16 v[32:35], v[194:197], v[210:213], v[32:35]
	v_mfma_f32_16x16x32_bf16 v[20:23], v[182:185], v[218:221], v[20:23]
	v_mfma_f32_16x16x32_bf16 v[16:19], v[194:197], v[218:221], v[16:19]
	v_mfma_f32_16x16x32_bf16 v[4:7], v[182:185], v[226:229], v[4:7]
	v_mfma_f32_16x16x32_bf16 v[0:3], v[194:197], v[226:229], v[0:3]
	s_setprio 0
	s_barrier
	v_add_u32_e32 v96, s74, v179
	v_add_u32_e32 v189, s75, v179
	ds_read_b128 v[76:79], v96
	ds_read_b128 v[84:87], v96 offset:1024
	ds_read_b128 v[88:91], v96 offset:2048
	ds_read_b128 v[96:99], v96 offset:3072
	ds_read_b128 v[172:175], v189
	ds_read_b128 v[182:185], v189 offset:1024
	ds_read_b128 v[190:193], v189 offset:2048
	ds_read_b128 v[194:197], v189 offset:3072
	s_add_u32 s56, s56, 0x100000
	s_addc_u32 s57, s57, 0
	s_mov_b32 m0, s70
	v_lshl_add_u64 v[234:235], s[56:57], 0, v[146:147]
	ds_read_b128 v[198:201], v181 offset:32768
	ds_read_b128 v[202:205], v181 offset:33792
	ds_read_b128 v[206:209], v181 offset:34816
	ds_read_b128 v[210:213], v181 offset:35840
	ds_read_b128 v[214:217], v181 offset:36864
	ds_read_b128 v[218:221], v181 offset:37888
	ds_read_b128 v[222:225], v181 offset:38912
	ds_read_b128 v[226:229], v181 offset:39936
	global_load_lds_dwordx4 v[234:235], off nt
	v_lshl_add_u64 v[234:235], s[56:57], 0, v[164:165]
	s_mov_b32 m0, s71
	s_nop 0
	global_load_lds_dwordx4 v[234:235], off nt
	s_waitcnt vmcnt(8)
	s_waitcnt lgkmcnt(0)
	s_barrier
	s_setprio 1
	s_waitcnt lgkmcnt(0)
	v_mfma_f32_16x16x32_bf16 v[140:143], v[76:79], v[198:201], v[140:143]
	v_mfma_f32_16x16x32_bf16 v[136:139], v[88:91], v[198:201], v[136:139]
	v_mfma_f32_16x16x32_bf16 v[124:127], v[76:79], v[206:209], v[124:127]
	v_mfma_f32_16x16x32_bf16 v[120:123], v[88:91], v[206:209], v[120:123]
	v_mfma_f32_16x16x32_bf16 v[108:111], v[76:79], v[214:217], v[108:111]
	v_mfma_f32_16x16x32_bf16 v[104:107], v[88:91], v[214:217], v[104:107]
	v_mfma_f32_16x16x32_bf16 v[80:83], v[76:79], v[222:225], v[80:83]
	v_mfma_f32_16x16x32_bf16 v[72:75], v[88:91], v[222:225], v[72:75]
	v_mfma_f32_16x16x32_bf16 v[140:143], v[84:87], v[202:205], v[140:143]
	v_mfma_f32_16x16x32_bf16 v[136:139], v[96:99], v[202:205], v[136:139]
	v_mfma_f32_16x16x32_bf16 v[124:127], v[84:87], v[210:213], v[124:127]
	v_mfma_f32_16x16x32_bf16 v[120:123], v[96:99], v[210:213], v[120:123]
	v_mfma_f32_16x16x32_bf16 v[108:111], v[84:87], v[218:221], v[108:111]
	v_mfma_f32_16x16x32_bf16 v[104:107], v[96:99], v[218:221], v[104:107]
	v_mfma_f32_16x16x32_bf16 v[80:83], v[84:87], v[226:229], v[80:83]
	v_mfma_f32_16x16x32_bf16 v[72:75], v[96:99], v[226:229], v[72:75]
	s_setprio 0
	s_setprio 1
	v_mfma_f32_16x16x32_bf16 v[132:135], v[172:175], v[198:201], v[132:135]
	v_mfma_f32_16x16x32_bf16 v[128:131], v[190:193], v[198:201], v[128:131]
	v_mfma_f32_16x16x32_bf16 v[116:119], v[172:175], v[206:209], v[116:119]
	v_mfma_f32_16x16x32_bf16 v[112:115], v[190:193], v[206:209], v[112:115]
	v_mfma_f32_16x16x32_bf16 v[100:103], v[172:175], v[214:217], v[100:103]
	v_mfma_f32_16x16x32_bf16 v[92:95], v[190:193], v[214:217], v[92:95]
	v_mfma_f32_16x16x32_bf16 v[68:71], v[172:175], v[222:225], v[68:71]
	v_mfma_f32_16x16x32_bf16 v[64:67], v[190:193], v[222:225], v[64:67]
	v_mfma_f32_16x16x32_bf16 v[132:135], v[182:185], v[202:205], v[132:135]
	v_mfma_f32_16x16x32_bf16 v[128:131], v[194:197], v[202:205], v[128:131]
	v_mfma_f32_16x16x32_bf16 v[116:119], v[182:185], v[210:213], v[116:119]
	v_mfma_f32_16x16x32_bf16 v[112:115], v[194:197], v[210:213], v[112:115]
	v_mfma_f32_16x16x32_bf16 v[100:103], v[182:185], v[218:221], v[100:103]
	v_mfma_f32_16x16x32_bf16 v[92:95], v[194:197], v[218:221], v[92:95]
	v_mfma_f32_16x16x32_bf16 v[68:71], v[182:185], v[226:229], v[68:71]
	v_mfma_f32_16x16x32_bf16 v[64:67], v[194:197], v[226:229], v[64:67]
	s_setprio 0
	s_barrier
	s_mov_b32 m0, s77
	v_lshl_add_u64 v[176:177], v[176:177], 0, s[8:9]
	s_add_u32 s16, s16, 0x40080
	ds_read_b128 v[198:201], v181 offset:49152
	ds_read_b128 v[202:205], v181 offset:50176
	ds_read_b128 v[206:209], v181 offset:51200
	ds_read_b128 v[210:213], v181 offset:52224
	ds_read_b128 v[214:217], v181 offset:53248
	ds_read_b128 v[218:221], v181 offset:54272
	ds_read_b128 v[222:225], v181 offset:55296
	ds_read_b128 v[226:229], v181 offset:56320
	global_load_lds_dwordx4 v[176:177], off
	v_lshl_add_u64 v[176:177], v[186:187], 0, s[8:9]
	s_mov_b32 m0, s78
	s_addc_u32 s17, s17, 0
	global_load_lds_dwordx4 v[176:177], off
	v_lshl_add_u64 v[176:177], s[16:17], 0, v[148:149]
	s_mov_b32 m0, s81
	s_nop 0
	global_load_lds_dwordx4 v[176:177], off
	v_lshl_add_u64 v[176:177], s[16:17], 0, v[166:167]
	s_mov_b32 m0, s82
	s_nop 0
	global_load_lds_dwordx4 v[176:177], off
	v_lshl_add_u64 v[176:177], v[230:231], 0, s[8:9]
	s_mov_b32 m0, s79
	s_nop 0
	global_load_lds_dwordx4 v[176:177], off nt
	v_lshl_add_u64 v[176:177], v[232:233], 0, s[8:9]
	s_mov_b32 m0, s80
	s_nop 0
	global_load_lds_dwordx4 v[176:177], off nt
	s_waitcnt vmcnt(8)
	s_waitcnt lgkmcnt(0)
	s_barrier
	s_setprio 1
	s_waitcnt lgkmcnt(0)
	v_mfma_f32_16x16x32_bf16 v[60:63], v[76:79], v[198:201], v[60:63]
	v_mfma_f32_16x16x32_bf16 v[56:59], v[88:91], v[198:201], v[56:59]
	v_mfma_f32_16x16x32_bf16 v[44:47], v[76:79], v[206:209], v[44:47]
	v_mfma_f32_16x16x32_bf16 v[40:43], v[88:91], v[206:209], v[40:43]
	v_mfma_f32_16x16x32_bf16 v[28:31], v[76:79], v[214:217], v[28:31]
	v_mfma_f32_16x16x32_bf16 v[24:27], v[88:91], v[214:217], v[24:27]
	v_mfma_f32_16x16x32_bf16 v[12:15], v[76:79], v[222:225], v[12:15]
	v_mfma_f32_16x16x32_bf16 v[8:11], v[88:91], v[222:225], v[8:11]
	v_mfma_f32_16x16x32_bf16 v[60:63], v[84:87], v[202:205], v[60:63]
	v_mfma_f32_16x16x32_bf16 v[56:59], v[96:99], v[202:205], v[56:59]
	v_mfma_f32_16x16x32_bf16 v[44:47], v[84:87], v[210:213], v[44:47]
	v_mfma_f32_16x16x32_bf16 v[40:43], v[96:99], v[210:213], v[40:43]
	v_mfma_f32_16x16x32_bf16 v[28:31], v[84:87], v[218:221], v[28:31]
	v_mfma_f32_16x16x32_bf16 v[24:27], v[96:99], v[218:221], v[24:27]
	v_mfma_f32_16x16x32_bf16 v[12:15], v[84:87], v[226:229], v[12:15]
	v_mfma_f32_16x16x32_bf16 v[8:11], v[96:99], v[226:229], v[8:11]
	s_setprio 0
	s_setprio 1
	v_mfma_f32_16x16x32_bf16 v[52:55], v[172:175], v[198:201], v[52:55]
	v_mfma_f32_16x16x32_bf16 v[48:51], v[190:193], v[198:201], v[48:51]
	v_mfma_f32_16x16x32_bf16 v[36:39], v[172:175], v[206:209], v[36:39]
	v_mfma_f32_16x16x32_bf16 v[32:35], v[190:193], v[206:209], v[32:35]
	v_mfma_f32_16x16x32_bf16 v[20:23], v[172:175], v[214:217], v[20:23]
	v_mfma_f32_16x16x32_bf16 v[16:19], v[190:193], v[214:217], v[16:19]
	v_mfma_f32_16x16x32_bf16 v[4:7], v[172:175], v[222:225], v[4:7]
	v_mfma_f32_16x16x32_bf16 v[0:3], v[190:193], v[222:225], v[0:3]
	v_mfma_f32_16x16x32_bf16 v[52:55], v[182:185], v[202:205], v[52:55]
	v_mfma_f32_16x16x32_bf16 v[48:51], v[194:197], v[202:205], v[48:51]
	v_mfma_f32_16x16x32_bf16 v[36:39], v[182:185], v[210:213], v[36:39]
	v_mfma_f32_16x16x32_bf16 v[32:35], v[194:197], v[210:213], v[32:35]
	v_mfma_f32_16x16x32_bf16 v[20:23], v[182:185], v[218:221], v[20:23]
	v_mfma_f32_16x16x32_bf16 v[16:19], v[194:197], v[218:221], v[16:19]
	v_mfma_f32_16x16x32_bf16 v[4:7], v[182:185], v[226:229], v[4:7]
	v_mfma_f32_16x16x32_bf16 v[0:3], v[194:197], v[226:229], v[0:3]
	s_setprio 0
	s_barrier
	s_add_i32 s89, s89, 2
	s_add_u32 s48, s48, 0x100
	s_addc_u32 s49, s49, 0
	s_add_u32 s87, s87, 0x100
	s_addc_u32 s88, s88, 0
	s_cmp_gt_u32 s89, 61
	s_cbranch_scc0 .LBB0_92
	s_and_b64 vcc, exec, s[4:5]
	s_cbranch_vccz .LBB0_95
	s_barrier
